# attention prefetch distance 2 tiles (two staging register sets)
# baseline (speedup 1.0000x reference)
; __device__ __forceinline__ unsigned cvtpk(float lo, float hi) { f32x2 v = {lo, hi}; bf16x2_t b = __builtin_convertvector(v, bf16x2_t); return *(unsigned*)&b; }
; __device__ __forceinline__ float lo16(unsigned w) { return __uint_as_float(w << 16); }
; __device__ __forceinline__ float hi16(unsigned w) { return __uint_as_float(w & 0xffff0000u); }
; #define SWAIT() asm volatile("s_waitcnt vmcnt(3)" ::: "memory")
; __device__ void phase_attn(const Params& p, char* lds) {
;     ...
;   for (int it = slot; it < nitems / 8; it += per) {
;     const int pair = (it >> 5) * 8 + xcd, qblk = it & 31;
;     const int b = pair >> 4, h = pair & 15;
;     const size_t row0 = (size_t)b * TL;
;     const size_t qrow = row0 + qblk * 256 + wid * 32 + r32;
;     const bf16_t* Kh = KVg + row0 * 2048 + h * 128;
;     const bf16_t* Kp = KPg + row0 * 32;
;     float m_reg = 0.f, l_reg = 0.f;
;     f32x16 o[2];
; #pragma unroll
;     for (int dd = 0; dd < 2; ++dd)
; #pragma unroll
;       for (int r = 0; r < 16; ++r) o[dd][r] = 0.f;
;     bf16x8 qr[6];
;     {
;       const bf16_t* Qw = Qg + qrow * 1536 + h * 96 + hi * 8;
; #pragma unroll
;       for (int d0 = 0; d0 < 6; ++d0) qr[d0] = *(const bf16x8*)(Qw + d0 * 16);
;       const int t = qblk * 256 + wid * 32 + r32;
;       const f32x2* tb = rope + (hi ? (t & 63) : (t >> 6)) * 8;
;       const u32x4 x1 = *(const u32x4*)&qr[4], x2 = *(const u32x4*)&qr[5];
;       u32x4 n1, n2;
; #pragma unroll
;       for (int q = 0; q < 4; ++q) {
;         const f32x2 csA = tb[2 * q], csB = tb[2 * q + 1];
;         const float a0 = lo16(x1[q]), a1 = hi16(x1[q]), b0 = lo16(x2[q]), b1 = hi16(x2[q]);
;         n1[q] = cvtpk(a0 * csA[0] - b0 * csA[1], a1 * csB[0] - b1 * csB[1]);
;         n2[q] = cvtpk(a0 * csA[1] + b0 * csA[0], a1 * csB[1] + b1 * csB[0]);
;       }
;       qr[4] = *(bf16x8*)&n1; qr[5] = *(bf16x8*)&n2;
;     }
;     struct { bf16x8 vs, ks, ps; } sr_[2];
;     ...
;     f32x16 pA0, pA1, pB0, pB1; float alA, alB; bf16x8 pa0, pa1, pa2, pa3;
;     constexpr int NT = TL / 64;
;     SLOAD(0, 0); asm volatile("s_waitcnt vmcnt(0)" ::: "memory"); SWRITE(0, 0); __syncthreads();
;     at_qkt(pA0, pA1, K_lds, qr, r32, hi, 0.f); at_partialSM(pA0, pA1, m_reg, alA, true);
;     SLOAD(1, 64); SLOAD(0, 128);
;     SWAIT(); SWRITE(1, 1); __syncthreads();
.Lat_item:
	s_lshr_b32 s16, s12, 5
	s_lshl_b32 s16, s16, 3
	s_add_i32 s16, s16, s43
	s_and_b32 s20, s12, 31
	s_lshr_b32 s22, s16, 4
	s_and_b32 s21, s16, 15
	s_mul_i32 s17, s22, 0x2100000
	s_lshl_b32 s18, s21, 8
	s_add_i32 s17, s17, s18
	s_add_u32 s17, s17, 0x29400000
	s_add_u32 s4, s86, s17
	s_addc_u32 s5, s87, 0
	s_mul_i32 s17, s22, 0x84000
	s_add_u32 s17, s17, 0x1de80000
	s_add_u32 s6, s86, s17
	s_addc_u32 s7, s87, 0
	s_mul_i32 s17, s22, 0x2100
	s_lshl_b32 s18, s20, 8
	s_add_i32 s17, s17, s18
	s_mul_i32 s18, s17, 0xc00
	s_mul_i32 s19, s21, 0xc0
	s_add_i32 s18, s18, s19
	s_add_u32 s18, s18, 0x8400000
	s_add_u32 s10, s86, s18
	s_addc_u32 s11, s87, 0
	s_lshl_b32 s18, s17, 11
	s_lshl_b32 s19, s21, 7
	s_add_i32 s18, s18, s19
	s_add_u32 s18, s18, 0x21000000
	s_add_u32 s28, s86, s18
	s_addc_u32 s29, s87, 0
	global_load_dwordx4 v[80:83], v234, s[10:11] offset:0
	global_load_dwordx4 v[84:87], v234, s[10:11] offset:32
	global_load_dwordx4 v[88:91], v234, s[10:11] offset:64
	global_load_dwordx4 v[92:95], v234, s[10:11] offset:96
	global_load_dwordx4 v[96:99], v234, s[10:11] offset:128
	global_load_dwordx4 v[100:103], v234, s[10:11] offset:160
	s_and_b32 s16, s14, 1
	s_lshl_b32 s16, s16, 5
	v_and_b32_e32 v183, 31, v178
	v_add_u32_e32 v183, s16, v183
	v_lshlrev_b32_e32 v183, 6, v183
	s_lshl_b32 s16, s20, 2
	s_lshr_b32 s17, s14, 1
	s_add_i32 s16, s16, s17
	s_lshl_b32 s16, s16, 6
	v_mov_b32_e32 v228, s16
	v_and_b32_e32 v229, 32, v178
	v_cmp_ne_u32_e32 vcc, 0, v229
	s_nop 1
	v_cndmask_b32_e32 v183, v228, v183, vcc
	global_load_dwordx4 v[32:35], v183, s[34:35] offset:0
	global_load_dwordx4 v[36:39], v183, s[34:35] offset:16
	global_load_dwordx4 v[40:43], v183, s[34:35] offset:32
	global_load_dwordx4 v[44:47], v183, s[34:35] offset:48
	s_barrier
	global_load_dwordx4 v[120:123], v129, s[4:5]
	global_load_dwordx4 v[124:127], v129, s[4:5] offset:128
	global_load_dwordx4 v[132:135], v130, s[6:7]
	s_add_u32 s4, s4, 0x40000
	s_addc_u32 s5, s5, 0
	s_add_u32 s6, s6, 0x1000
	s_addc_u32 s7, s7, 0
	global_load_dwordx4 v[136:139], v129, s[4:5]
	global_load_dwordx4 v[140:143], v129, s[4:5] offset:128
	global_load_dwordx4 v[144:147], v130, s[6:7]
	s_add_u32 s4, s4, 0x40000
	s_addc_u32 s5, s5, 0
	s_add_u32 s6, s6, 0x1000
	s_addc_u32 s7, s7, 0
	s_waitcnt vmcnt(0)
	ds_write_b128 v167, v[120:123] offset:0
	ds_write_b128 v131, v[124:127] offset:0
	ds_write_b128 v169, v[132:135] offset:0
	ds_write_b128 v167, v[136:139] offset:13312
	ds_write_b128 v131, v[140:143] offset:16384
	ds_write_b128 v169, v[144:147] offset:13312
	s_waitcnt lgkmcnt(0)
	global_load_dwordx4 v[120:123], v129, s[4:5]
	global_load_dwordx4 v[124:127], v129, s[4:5] offset:128
	global_load_dwordx4 v[132:135], v130, s[6:7]
	s_add_u32 s4, s4, 0x40000
	s_addc_u32 s5, s5, 0
	s_add_u32 s6, s6, 0x1000
	s_addc_u32 s7, s7, 0
	global_load_dwordx4 v[136:139], v129, s[4:5]
	global_load_dwordx4 v[140:143], v129, s[4:5] offset:128
	global_load_dwordx4 v[144:147], v130, s[6:7]
	s_add_u32 s4, s4, 0x40000
	s_addc_u32 s5, s5, 0
	s_add_u32 s6, s6, 0x1000
	s_addc_u32 s7, s7, 0
	v_lshlrev_b32_e32 v175, 16, v96
	v_and_b32_e32 v183, 0xffff0000, v96
	v_lshlrev_b32_e32 v228, 16, v100
	v_and_b32_e32 v229, 0xffff0000, v100
	v_mul_f32_e32 v230, v228, v33
	v_mul_f32_e32 v174, v229, v35
	v_fma_f32 v230, v175, v32, -v230
	v_fma_f32 v174, v183, v34, -v174
	v_mul_f32_e32 v175, v175, v33
	v_mul_f32_e32 v183, v183, v35
	v_fma_f32 v175, v228, v32, v175
	v_fma_f32 v183, v229, v34, v183
	v_cvt_pk_bf16_f32 v96, v230, v174
	v_cvt_pk_bf16_f32 v100, v175, v183
	v_lshlrev_b32_e32 v175, 16, v97
	v_and_b32_e32 v183, 0xffff0000, v97
	v_lshlrev_b32_e32 v228, 16, v101
	v_and_b32_e32 v229, 0xffff0000, v101
	v_mul_f32_e32 v230, v228, v37
	v_mul_f32_e32 v174, v229, v39
	v_fma_f32 v230, v175, v36, -v230
	v_fma_f32 v174, v183, v38, -v174
	v_mul_f32_e32 v175, v175, v37
	v_mul_f32_e32 v183, v183, v39
	v_fma_f32 v175, v228, v36, v175
	v_fma_f32 v183, v229, v38, v183
	v_cvt_pk_bf16_f32 v97, v230, v174
	v_cvt_pk_bf16_f32 v101, v175, v183
	v_lshlrev_b32_e32 v175, 16, v98
	v_and_b32_e32 v183, 0xffff0000, v98
	v_lshlrev_b32_e32 v228, 16, v102
	v_and_b32_e32 v229, 0xffff0000, v102
	v_mul_f32_e32 v230, v228, v41
	v_mul_f32_e32 v174, v229, v43
	v_fma_f32 v230, v175, v40, -v230
	v_fma_f32 v174, v183, v42, -v174
	v_mul_f32_e32 v175, v175, v41
	v_mul_f32_e32 v183, v183, v43
	v_fma_f32 v175, v228, v40, v175
	v_fma_f32 v183, v229, v42, v183
	v_cvt_pk_bf16_f32 v98, v230, v174
	v_cvt_pk_bf16_f32 v102, v175, v183
	v_lshlrev_b32_e32 v175, 16, v99
	v_and_b32_e32 v183, 0xffff0000, v99
	v_lshlrev_b32_e32 v228, 16, v103
	v_and_b32_e32 v229, 0xffff0000, v103
	v_mul_f32_e32 v230, v228, v45
	v_mul_f32_e32 v174, v229, v47
	v_fma_f32 v230, v175, v44, -v230
	v_fma_f32 v174, v183, v46, -v174
	v_mul_f32_e32 v175, v175, v45
	v_mul_f32_e32 v183, v183, v47
	v_fma_f32 v175, v228, v44, v175
	v_fma_f32 v183, v229, v46, v183
	v_cvt_pk_bf16_f32 v99, v230, v174
	v_cvt_pk_bf16_f32 v103, v175, v183
	v_mov_b32_e32 v0, 0
	v_mov_b32_e32 v1, 0
	v_mov_b32_e32 v2, 0
	v_mov_b32_e32 v3, 0
	v_mov_b32_e32 v4, 0
	v_mov_b32_e32 v5, 0
	v_mov_b32_e32 v6, 0
	v_mov_b32_e32 v7, 0
	v_mov_b32_e32 v8, 0
	v_mov_b32_e32 v9, 0
	v_mov_b32_e32 v10, 0
	v_mov_b32_e32 v11, 0
	v_mov_b32_e32 v12, 0
	v_mov_b32_e32 v13, 0
	v_mov_b32_e32 v14, 0
	v_mov_b32_e32 v15, 0
	v_mov_b32_e32 v16, 0
	v_mov_b32_e32 v17, 0
	v_mov_b32_e32 v18, 0
	v_mov_b32_e32 v19, 0
	v_mov_b32_e32 v20, 0
	v_mov_b32_e32 v21, 0
	v_mov_b32_e32 v22, 0
	v_mov_b32_e32 v23, 0
	v_mov_b32_e32 v24, 0
	v_mov_b32_e32 v25, 0
	v_mov_b32_e32 v26, 0
	v_mov_b32_e32 v27, 0
	v_mov_b32_e32 v28, 0
	v_mov_b32_e32 v29, 0
	v_mov_b32_e32 v30, 0
	v_mov_b32_e32 v31, 0
	v_mov_b32_e32 v173, 0
	s_barrier
	ds_read_b128 v[184:187], v170 offset:0
	ds_read_b128 v[188:191], v170 offset:6656
	ds_read_b128 v[192:195], v170 offset:32
	ds_read_b128 v[196:199], v170 offset:6688
	s_cmp_eq_u32 s15, 0
	s_cbranch_scc1 .Lat_nostag
	s_barrier
; #define SLOAD(i, k0) do { sr_[i].vs = *(const bf16x8*)(Kh + (size_t)((k0) + skey) * 2048 + 64 + sc8); \
;     sr_[i].ks = *(const bf16x8*)(Kh + (size_t)((k0) + skey) * 2048 + sc8); \
;     sr_[i].ps = *(const bf16x8*)(Kp + (size_t)((k0) + pkey) * 32 + pc8); } while (0)
; #define SWRITE(bb, i) do { *(bf16x8*)(V_lds + (bb) * AT_SHMV + vst) = sr_[i].vs; \
;     *(bf16x8*)(K_lds + (bb) * AT_SHMK + kst) = sr_[i].ks; \
;     *(bf16x8*)(K_lds + (bb) * AT_SHMK + pst) = sr_[i].ps; } while (0)
; __device__ __forceinline__ void at_partialSM(f32x16& p0, f32x16& p1, float& m_reg, float& alpha, bool force) {
;   float pm = p0[0];
; #pragma unroll
;   for (int r = 1; r < 16; ++r) pm = fmaxf(pm, p0[r]);
; #pragma unroll
;   for (int r = 0; r < 16; ++r) pm = fmaxf(pm, p1[r]);
;   { auto rr = __builtin_amdgcn_permlane32_swap(__float_as_uint(pm), __float_as_uint(pm), false, false);
;     pm = fmaxf(__uint_as_float(rr[0]), __uint_as_float(rr[1])); }
;   if (__builtin_expect(!force && __all(pm <= AT_THR * 1.4426950408889634f), 1)) { alpha = 1.f; }
;   else {
;     const float dlt = force ? pm : fmaxf(pm, 0.f);
;     alpha = force ? 1.f : __builtin_amdgcn_exp2f(-dlt); m_reg += dlt;
; #pragma unroll
;     for (int r = 0; r < 16; ++r) { p0[r] -= dlt; p1[r] -= dlt; }
;   }
; #pragma unroll
;   for (int r = 0; r < 16; ++r) p0[r] = __builtin_amdgcn_exp2f(p0[r]);
; }
; __device__ __forceinline__ void at_finishSM(f32x16& p0, f32x16& p1, float alpha, float& l_reg, bf16x8& pa0, bf16x8& pa1, bf16x8& pa2, bf16x8& pa3) {
; #pragma unroll
;   for (int r = 0; r < 16; ++r) p1[r] = __builtin_amdgcn_exp2f(p1[r]);
;   float ps = 0;
; #pragma unroll
;   for (int r = 0; r < 16; ++r) ps += p0[r];
; #pragma unroll
;   for (int r = 0; r < 16; ++r) ps += p1[r];
;   { auto rr = __builtin_amdgcn_permlane32_swap(__float_as_uint(ps), __float_as_uint(ps), false, false);
;     ps = __uint_as_float(rr[0]) + __uint_as_float(rr[1]); }
;   l_reg = l_reg * alpha + ps;
;     ...
;   PK4(p0, 0, pa0); PK4(p0, 8, pa1); PK4(p1, 0, pa2); PK4(p1, 8, pa3);
;     ...
; }
; __device__ void phase_attn(const Params& p, char* lds) {
;     ...
;     SLOAD(0, 0); asm volatile("s_waitcnt vmcnt(0)" ::: "memory"); SWRITE(0, 0); __syncthreads();
;     at_qkt(pA0, pA1, K_lds, qr, r32, hi, 0.f); at_partialSM(pA0, pA1, m_reg, alA, true);
;     SLOAD(1, 64); SLOAD(0, 128);
;     SWAIT(); SWRITE(1, 1); __syncthreads();
.Lat_nostag:
	ds_read_b128 v[200:203], v170 offset:64
	ds_read_b128 v[204:207], v170 offset:6720
	s_waitcnt lgkmcnt(4)
	v_mfma_f32_32x32x16_bf16 v[32:47], v[184:187], v[80:83], 0
	v_mfma_f32_32x32x16_bf16 v[48:63], v[188:191], v[80:83], 0
	ds_read_b128 v[208:211], v170 offset:96
	ds_read_b128 v[212:215], v170 offset:6752
	s_waitcnt lgkmcnt(4)
	v_mfma_f32_32x32x16_bf16 v[32:47], v[192:195], v[84:87], v[32:47]
	v_mfma_f32_32x32x16_bf16 v[48:63], v[196:199], v[84:87], v[48:63]
	ds_read_b128 v[184:187], v170 offset:128
	ds_read_b128 v[188:191], v170 offset:6784
	s_waitcnt lgkmcnt(4)
	v_mfma_f32_32x32x16_bf16 v[32:47], v[200:203], v[88:91], v[32:47]
	v_mfma_f32_32x32x16_bf16 v[48:63], v[204:207], v[88:91], v[48:63]
	ds_read_b128 v[192:195], v170 offset:160
	ds_read_b128 v[196:199], v170 offset:6816
	s_waitcnt lgkmcnt(4)
	v_mfma_f32_32x32x16_bf16 v[32:47], v[208:211], v[92:95], v[32:47]
	v_mfma_f32_32x32x16_bf16 v[48:63], v[212:215], v[92:95], v[48:63]
	s_waitcnt lgkmcnt(2)
	v_mfma_f32_32x32x16_bf16 v[32:47], v[184:187], v[96:99], v[32:47]
	v_mfma_f32_32x32x16_bf16 v[48:63], v[188:191], v[96:99], v[48:63]
	s_waitcnt lgkmcnt(0)
	v_mfma_f32_32x32x16_bf16 v[32:47], v[192:195], v[100:103], v[32:47]
	v_mfma_f32_32x32x16_bf16 v[48:63], v[196:199], v[100:103], v[48:63]
	s_nop 11
	v_max3_f32 v174, v32, v33, v34
	v_max3_f32 v175, v48, v49, v50
	v_max3_f32 v174, v174, v35, v36
	v_max3_f32 v175, v175, v51, v52
	v_max3_f32 v174, v174, v37, v38
	v_max3_f32 v175, v175, v53, v54
	v_max3_f32 v174, v174, v39, v40
	v_max3_f32 v175, v175, v55, v56
	v_max3_f32 v174, v174, v41, v42
	v_max3_f32 v175, v175, v57, v58
	v_max3_f32 v174, v174, v43, v44
	v_max3_f32 v175, v175, v59, v60
	v_max3_f32 v174, v174, v45, v46
	v_max3_f32 v175, v175, v61, v62
	v_max3_f32 v174, v174, v47, v63
	v_max_f32_e32 v174, v174, v175
	v_mov_b32_e32 v175, v174
	s_nop 1
	v_permlane32_swap_b32_e32 v174, v175
	v_max_f32_e32 v174, v174, v175
	s_barrier
	v_mov_b32_e32 v172, v174
	v_sub_f32_e32 v32, v32, v174
	v_sub_f32_e32 v48, v48, v174
	v_sub_f32_e32 v33, v33, v174
	v_sub_f32_e32 v49, v49, v174
	v_sub_f32_e32 v34, v34, v174
	v_sub_f32_e32 v50, v50, v174
	v_sub_f32_e32 v35, v35, v174
	v_sub_f32_e32 v51, v51, v174
	v_sub_f32_e32 v36, v36, v174
	v_sub_f32_e32 v52, v52, v174
	v_sub_f32_e32 v37, v37, v174
	v_sub_f32_e32 v53, v53, v174
	v_sub_f32_e32 v38, v38, v174
	v_sub_f32_e32 v54, v54, v174
	v_sub_f32_e32 v39, v39, v174
	v_sub_f32_e32 v55, v55, v174
	v_sub_f32_e32 v40, v40, v174
	v_sub_f32_e32 v56, v56, v174
	v_sub_f32_e32 v41, v41, v174
	v_sub_f32_e32 v57, v57, v174
	v_sub_f32_e32 v42, v42, v174
	v_sub_f32_e32 v58, v58, v174
	v_sub_f32_e32 v43, v43, v174
	v_sub_f32_e32 v59, v59, v174
	v_sub_f32_e32 v44, v44, v174
	v_sub_f32_e32 v60, v60, v174
	v_sub_f32_e32 v45, v45, v174
	v_sub_f32_e32 v61, v61, v174
	v_sub_f32_e32 v46, v46, v174
	v_sub_f32_e32 v62, v62, v174
	v_sub_f32_e32 v47, v47, v174
	v_sub_f32_e32 v63, v63, v174
	v_sub_f32_e32 v64, 0, v174
	v_sub_f32_e32 v65, 0, v174
	v_sub_f32_e32 v66, 0, v174
	v_sub_f32_e32 v67, 0, v174
	v_sub_f32_e32 v68, 0, v174
	v_sub_f32_e32 v69, 0, v174
	v_sub_f32_e32 v70, 0, v174
	v_sub_f32_e32 v71, 0, v174
	v_sub_f32_e32 v72, 0, v174
	v_sub_f32_e32 v73, 0, v174
	v_sub_f32_e32 v74, 0, v174
	v_sub_f32_e32 v75, 0, v174
	v_sub_f32_e32 v76, 0, v174
	v_sub_f32_e32 v77, 0, v174
	v_sub_f32_e32 v78, 0, v174
	v_sub_f32_e32 v79, 0, v174
	s_waitcnt vmcnt(3)
	ds_write_b128 v167, v[120:123] offset:26624
	ds_write_b128 v131, v[124:127] offset:32768
	ds_write_b128 v169, v[132:135] offset:26624
	v_exp_f32_e32 v32, v32
	v_exp_f32_e32 v48, v48
	v_exp_f32_e32 v33, v33
	v_exp_f32_e32 v49, v49
	v_exp_f32_e32 v34, v34
	v_exp_f32_e32 v50, v50
	v_exp_f32_e32 v35, v35
	v_exp_f32_e32 v51, v51
	v_exp_f32_e32 v36, v36
	v_exp_f32_e32 v52, v52
	v_exp_f32_e32 v37, v37
	v_exp_f32_e32 v53, v53
	v_exp_f32_e32 v38, v38
	v_exp_f32_e32 v54, v54
	v_exp_f32_e32 v39, v39
	v_exp_f32_e32 v55, v55
	v_exp_f32_e32 v40, v40
	v_exp_f32_e32 v56, v56
	v_exp_f32_e32 v41, v41
	v_exp_f32_e32 v57, v57
	v_exp_f32_e32 v42, v42
	v_exp_f32_e32 v58, v58
	v_exp_f32_e32 v43, v43
	v_exp_f32_e32 v59, v59
	v_exp_f32_e32 v44, v44
	v_exp_f32_e32 v60, v60
	v_exp_f32_e32 v45, v45
	v_exp_f32_e32 v61, v61
	v_exp_f32_e32 v46, v46
	v_exp_f32_e32 v62, v62
	v_exp_f32_e32 v47, v47
	v_exp_f32_e32 v63, v63
	s_waitcnt lgkmcnt(0)
	global_load_dwordx4 v[120:123], v129, s[4:5]
	global_load_dwordx4 v[124:127], v129, s[4:5] offset:128
	global_load_dwordx4 v[132:135], v130, s[6:7]
	s_add_u32 s4, s4, 0x40000
	s_addc_u32 s5, s5, 0
	s_add_u32 s6, s6, 0x1000
	s_addc_u32 s7, s7, 0
	v_add_f32_e32 v175, v32, v33
	v_add_f32_e32 v174, v48, v49
	v_add_f32_e32 v175, v175, v34
	v_add_f32_e32 v174, v174, v50
	v_add_f32_e32 v175, v175, v35
	v_add_f32_e32 v174, v174, v51
	v_add_f32_e32 v175, v175, v36
	v_add_f32_e32 v174, v174, v52
	v_add_f32_e32 v175, v175, v37
	v_add_f32_e32 v174, v174, v53
	v_add_f32_e32 v175, v175, v38
	v_add_f32_e32 v174, v174, v54
	v_add_f32_e32 v175, v175, v39
	v_add_f32_e32 v174, v174, v55
	v_add_f32_e32 v175, v175, v40
	v_add_f32_e32 v174, v174, v56
	v_add_f32_e32 v175, v175, v41
	v_add_f32_e32 v174, v174, v57
	v_add_f32_e32 v175, v175, v42
	v_add_f32_e32 v174, v174, v58
	v_add_f32_e32 v175, v175, v43
	v_add_f32_e32 v174, v174, v59
	v_add_f32_e32 v175, v175, v44
	v_add_f32_e32 v174, v174, v60
	v_add_f32_e32 v175, v175, v45
	v_add_f32_e32 v174, v174, v61
	v_add_f32_e32 v175, v175, v46
	v_add_f32_e32 v174, v174, v62
	v_add_f32_e32 v175, v175, v47
	v_add_f32_e32 v174, v174, v63
	v_add_f32_e32 v175, v175, v174
	v_add_f32_e32 v173, v173, v175
	v_cvt_pk_bf16_f32 v104, v32, v33
	v_cvt_pk_bf16_f32 v105, v34, v35
	v_cvt_pk_bf16_f32 v106, v36, v37
	v_cvt_pk_bf16_f32 v107, v38, v39
	v_cvt_pk_bf16_f32 v108, v40, v41
	v_cvt_pk_bf16_f32 v109, v42, v43
	v_cvt_pk_bf16_f32 v110, v44, v45
	v_cvt_pk_bf16_f32 v111, v46, v47
	v_cvt_pk_bf16_f32 v112, v48, v49
	v_cvt_pk_bf16_f32 v113, v50, v51
	v_cvt_pk_bf16_f32 v114, v52, v53
	v_cvt_pk_bf16_f32 v115, v54, v55
	v_cvt_pk_bf16_f32 v116, v56, v57
	v_cvt_pk_bf16_f32 v117, v58, v59
	v_cvt_pk_bf16_f32 v118, v60, v61
	v_cvt_pk_bf16_f32 v119, v62, v63
	ds_read_b128 v[184:187], v170 offset:13312
	ds_read_b128 v[188:191], v170 offset:19968
	ds_read_b128 v[192:195], v170 offset:13344
	ds_read_b128 v[196:199], v170 offset:20000
	s_barrier
	s_mov_b32 s13, 32
; __device__ __forceinline__ void at_finishSM(f32x16& p0, f32x16& p1, float alpha, float& l_reg, bf16x8& pa0, bf16x8& pa1, bf16x8& pa2, bf16x8& pa3) {
; #pragma unroll
;   for (int r = 0; r < 16; ++r) p1[r] = __builtin_amdgcn_exp2f(p1[r]);
;   float ps = 0;
; #pragma unroll
;   for (int r = 0; r < 16; ++r) ps += p0[r];
; #pragma unroll
;   for (int r = 0; r < 16; ++r) ps += p1[r];
;   { auto rr = __builtin_amdgcn_permlane32_swap(__float_as_uint(ps), __float_as_uint(ps), false, false);
;     ps = __uint_as_float(rr[0]) + __uint_as_float(rr[1]); }
;   l_reg = l_reg * alpha + ps;
;     ...
;   PK4(p0, 0, pa0); PK4(p0, 8, pa1); PK4(p1, 0, pa2); PK4(p1, 8, pa3);
;     ...
; }
; __device__ __forceinline__ void at_qkt(f32x16& p0, f32x16& p1, const char* Ks, const bf16x8* qr, int r32, int hi, float negm) {
; #pragma unroll
;   for (int r = 0; r < 16; ++r) { p0[r] = negm; p1[r] = negm; }
; #pragma unroll
;   for (int d0 = 0; d0 < 6; ++d0) {
;     const bf16x8 b0 = *(const bf16x8*)(Ks + r32 * AT_KROW + d0 * 32 + hi * 16);
;     const bf16x8 b1 = *(const bf16x8*)(Ks + (32 + r32) * AT_KROW + d0 * 32 + hi * 16);
;     p0 = MFMA(b0, qr[d0], p0);
;     p1 = MFMA(b1, qr[d0], p1);
;   }
; }
; __device__ __forceinline__ int v_st(int k, int c) { const int kk = (k & ~0xC) | ((k & 4) << 1) | ((k & 8) >> 1); return ((kk >> 3) * 4 + (c >> 5)) * 512 + ((kk & 7) * 32 + (c & 31)) * 2; }
; __device__ __forceinline__ int v_rd_base(int lane) { return ((lane & 3) << 3) | (((lane >> 2) & 3) << 6) | (((lane >> 4) & 1) << 5) | (((lane >> 5) & 1) << 8); }
; __device__ void phase_attn(const Params& p, char* lds) {
;     ...
;     for (int j = 1; j + 1 < NT; j += 2) {
;       SBAR(); at_qkt(pB0, pB1, K_lds + AT_SHMK, qr, r32, hi, -m_reg);
;       at_finishSM(pA0, pA1, alA, l_reg, pa0, pa1, pa2, pa3); SBAR();
;       SLOAD(1, (j + 2) * 64); SBAR();
;       pv_d0(o, vb0, pa0, pa1, pa2, pa3); at_partialSM(pB0, pB1, m_reg, alB, false);
;       __syncthreads(); SWAIT(); SWRITE(0, 0);
;       RESC(alB); __syncthreads();
;       SBAR(); at_qkt(pA0, pA1, K_lds, qr, r32, hi, -m_reg);
;       at_finishSM(pB0, pB1, alB, l_reg, pa0, pa1, pa2, pa3); SBAR();
;       if (j + 3 < NT) SLOAD(0, (j + 3) * 64); SBAR();
;       pv_d0(o, vb0 + AT_SHMV, pa0, pa1, pa2, pa3); at_partialSM(pA0, pA1, m_reg, alA, false);
;       __syncthreads(); SWAIT(); SWRITE(1, 1);
;       RESC(alA); __syncthreads();
.Lat_loop:
	ds_read_b128 v[200:203], v170 offset:13376
	ds_read_b128 v[204:207], v170 offset:20032
	s_waitcnt lgkmcnt(4)
	v_mfma_f32_32x32x16_bf16 v[32:47], v[184:187], v[80:83], v[64:79]
	v_mfma_f32_32x32x16_bf16 v[48:63], v[188:191], v[80:83], v[64:79]
	ds_read_b128 v[208:211], v170 offset:13408
	ds_read_b128 v[212:215], v170 offset:20064
	s_waitcnt lgkmcnt(4)
	v_mfma_f32_32x32x16_bf16 v[32:47], v[192:195], v[84:87], v[32:47]
	v_mfma_f32_32x32x16_bf16 v[48:63], v[196:199], v[84:87], v[48:63]
	ds_read_b128 v[184:187], v170 offset:13440
	ds_read_b128 v[188:191], v170 offset:20096
	s_waitcnt lgkmcnt(4)
	v_mfma_f32_32x32x16_bf16 v[32:47], v[200:203], v[88:91], v[32:47]
	v_mfma_f32_32x32x16_bf16 v[48:63], v[204:207], v[88:91], v[48:63]
	ds_read_b128 v[192:195], v170 offset:13472
	ds_read_b128 v[196:199], v170 offset:20128
	s_waitcnt lgkmcnt(4)
	v_mfma_f32_32x32x16_bf16 v[32:47], v[208:211], v[92:95], v[32:47]
	v_mfma_f32_32x32x16_bf16 v[48:63], v[212:215], v[92:95], v[48:63]
	ds_read_b64_tr_b16 v[148:149], v171 offset:0
	ds_read_b64_tr_b16 v[150:151], v171 offset:2048
	ds_read_b64_tr_b16 v[152:153], v171 offset:4096
	ds_read_b64_tr_b16 v[154:155], v171 offset:6144
	s_waitcnt lgkmcnt(6)
	v_mfma_f32_32x32x16_bf16 v[32:47], v[184:187], v[96:99], v[32:47]
	v_mfma_f32_32x32x16_bf16 v[48:63], v[188:191], v[96:99], v[48:63]
	ds_read_b64_tr_b16 v[156:157], v171 offset:8192
	ds_read_b64_tr_b16 v[158:159], v171 offset:10240
	ds_read_b64_tr_b16 v[216:217], v171 offset:12288
	ds_read_b64_tr_b16 v[218:219], v171 offset:14336
	s_waitcnt lgkmcnt(8)
	v_mfma_f32_32x32x16_bf16 v[32:47], v[192:195], v[100:103], v[32:47]
	v_mfma_f32_32x32x16_bf16 v[48:63], v[196:199], v[100:103], v[48:63]
	ds_read_b64_tr_b16 v[220:221], v171 offset:512
	ds_read_b64_tr_b16 v[222:223], v171 offset:2560
	ds_read_b64_tr_b16 v[224:225], v171 offset:4608
	ds_read_b64_tr_b16 v[226:227], v171 offset:6656
	s_waitcnt lgkmcnt(10)
	v_mfma_f32_32x32x16_bf16 v[0:15], v[104:107], v[148:151], v[0:15]
	s_waitcnt lgkmcnt(8)
	v_mfma_f32_32x32x16_bf16 v[0:15], v[108:111], v[152:155], v[0:15]
	ds_read_b64_tr_b16 v[236:237], v171 offset:8704
	ds_read_b64_tr_b16 v[238:239], v171 offset:10752
	ds_read_b64_tr_b16 v[240:241], v171 offset:12800
	ds_read_b64_tr_b16 v[242:243], v171 offset:14848
	s_waitcnt lgkmcnt(10)
	v_mfma_f32_32x32x16_bf16 v[0:15], v[112:115], v[156:159], v[0:15]
	s_waitcnt lgkmcnt(8)
	v_mfma_f32_32x32x16_bf16 v[0:15], v[116:119], v[216:219], v[0:15]
	s_waitcnt lgkmcnt(6)
	v_mfma_f32_32x32x16_bf16 v[16:31], v[104:107], v[220:223], v[16:31]
	s_waitcnt lgkmcnt(4)
	v_mfma_f32_32x32x16_bf16 v[16:31], v[108:111], v[224:227], v[16:31]
	s_waitcnt lgkmcnt(2)
	v_mfma_f32_32x32x16_bf16 v[16:31], v[112:115], v[236:239], v[16:31]
	s_waitcnt lgkmcnt(0)
	v_mfma_f32_32x32x16_bf16 v[16:31], v[116:119], v[240:243], v[16:31]
	s_barrier
	s_waitcnt vmcnt(3)
	ds_write_b128 v167, v[136:139] offset:39936
	ds_write_b128 v131, v[140:143] offset:49152
	ds_write_b128 v169, v[144:147] offset:39936
	v_exp_f32_e32 v32, v32
	v_exp_f32_e32 v48, v48
	v_exp_f32_e32 v33, v33
	v_exp_f32_e32 v49, v49
	v_exp_f32_e32 v34, v34
	v_exp_f32_e32 v50, v50
	v_exp_f32_e32 v35, v35
	v_exp_f32_e32 v51, v51
	v_exp_f32_e32 v36, v36
	v_exp_f32_e32 v52, v52
	v_exp_f32_e32 v37, v37
	v_exp_f32_e32 v53, v53
	v_exp_f32_e32 v38, v38
	v_exp_f32_e32 v54, v54
	v_exp_f32_e32 v39, v39
	v_exp_f32_e32 v55, v55
	v_exp_f32_e32 v40, v40
	v_exp_f32_e32 v56, v56
	v_exp_f32_e32 v41, v41
	v_exp_f32_e32 v57, v57
	v_exp_f32_e32 v42, v42
	v_exp_f32_e32 v58, v58
	v_exp_f32_e32 v43, v43
	v_exp_f32_e32 v59, v59
	v_exp_f32_e32 v44, v44
	v_exp_f32_e32 v60, v60
	v_exp_f32_e32 v45, v45
	v_exp_f32_e32 v61, v61
	v_exp_f32_e32 v46, v46
	v_exp_f32_e32 v62, v62
	v_exp_f32_e32 v47, v47
	v_exp_f32_e32 v63, v63
	s_waitcnt lgkmcnt(0)
	global_load_dwordx4 v[136:139], v129, s[4:5]
	global_load_dwordx4 v[140:143], v129, s[4:5] offset:128
	global_load_dwordx4 v[144:147], v130, s[6:7]
	s_add_u32 s4, s4, 0x40000
	s_addc_u32 s5, s5, 0
	s_add_u32 s6, s6, 0x1000
	s_addc_u32 s7, s7, 0
	v_add_f32_e32 v175, v32, v33
	v_add_f32_e32 v174, v48, v49
	v_add_f32_e32 v175, v175, v34
	v_add_f32_e32 v174, v174, v50
	v_add_f32_e32 v175, v175, v35
	v_add_f32_e32 v174, v174, v51
	v_add_f32_e32 v175, v175, v36
	v_add_f32_e32 v174, v174, v52
	v_add_f32_e32 v175, v175, v37
	v_add_f32_e32 v174, v174, v53
	v_add_f32_e32 v175, v175, v38
	v_add_f32_e32 v174, v174, v54
	v_add_f32_e32 v175, v175, v39
	v_add_f32_e32 v174, v174, v55
	v_add_f32_e32 v175, v175, v40
	v_add_f32_e32 v174, v174, v56
	v_add_f32_e32 v175, v175, v41
	v_add_f32_e32 v174, v174, v57
	v_add_f32_e32 v175, v175, v42
	v_add_f32_e32 v174, v174, v58
	v_add_f32_e32 v175, v175, v43
	v_add_f32_e32 v174, v174, v59
	v_add_f32_e32 v175, v175, v44
	v_add_f32_e32 v174, v174, v60
	v_add_f32_e32 v175, v175, v45
	v_add_f32_e32 v174, v174, v61
	v_add_f32_e32 v175, v175, v46
	v_add_f32_e32 v174, v174, v62
	v_add_f32_e32 v175, v175, v47
	v_add_f32_e32 v174, v174, v63
	v_add_f32_e32 v175, v175, v174
	v_cmp_ge_f32_e32 vcc, s23, v175
	s_cmp_eq_u64 vcc, exec
	s_cbranch_scc0 .Lat_rare0
; __device__ __forceinline__ void at_finishSM(f32x16& p0, f32x16& p1, float alpha, float& l_reg, bf16x8& pa0, bf16x8& pa1, bf16x8& pa2, bf16x8& pa3) {
; #pragma unroll
;   for (int r = 0; r < 16; ++r) p1[r] = __builtin_amdgcn_exp2f(p1[r]);
;   float ps = 0;
; #pragma unroll
;   for (int r = 0; r < 16; ++r) ps += p0[r];
; #pragma unroll
;   for (int r = 0; r < 16; ++r) ps += p1[r];
;   { auto rr = __builtin_amdgcn_permlane32_swap(__float_as_uint(ps), __float_as_uint(ps), false, false);
;     ps = __uint_as_float(rr[0]) + __uint_as_float(rr[1]); }
;   l_reg = l_reg * alpha + ps;
;     ...
;   PK4(p0, 0, pa0); PK4(p0, 8, pa1); PK4(p1, 0, pa2); PK4(p1, 8, pa3);
;     ...
; }
; __device__ __forceinline__ void at_qkt(f32x16& p0, f32x16& p1, const char* Ks, const bf16x8* qr, int r32, int hi, float negm) {
; #pragma unroll
;   for (int r = 0; r < 16; ++r) { p0[r] = negm; p1[r] = negm; }
; #pragma unroll
;   for (int d0 = 0; d0 < 6; ++d0) {
;     const bf16x8 b0 = *(const bf16x8*)(Ks + r32 * AT_KROW + d0 * 32 + hi * 16);
;     const bf16x8 b1 = *(const bf16x8*)(Ks + (32 + r32) * AT_KROW + d0 * 32 + hi * 16);
;     p0 = MFMA(b0, qr[d0], p0);
;     p1 = MFMA(b1, qr[d0], p1);
;   }
; }
; __device__ __forceinline__ int v_st(int k, int c) { const int kk = (k & ~0xC) | ((k & 4) << 1) | ((k & 8) >> 1); return ((kk >> 3) * 4 + (c >> 5)) * 512 + ((kk & 7) * 32 + (c & 31)) * 2; }
; __device__ __forceinline__ int v_rd_base(int lane) { return ((lane & 3) << 3) | (((lane >> 2) & 3) << 6) | (((lane >> 4) & 1) << 5) | (((lane >> 5) & 1) << 8); }
; __device__ void phase_attn(const Params& p, char* lds) {
;     ...
;     for (int j = 1; j + 1 < NT; j += 2) {
;       SBAR(); at_qkt(pB0, pB1, K_lds + AT_SHMK, qr, r32, hi, -m_reg);
;       at_finishSM(pA0, pA1, alA, l_reg, pa0, pa1, pa2, pa3); SBAR();
;       SLOAD(1, (j + 2) * 64); SBAR();
;       pv_d0(o, vb0, pa0, pa1, pa2, pa3); at_partialSM(pB0, pB1, m_reg, alB, false);
;       __syncthreads(); SWAIT(); SWRITE(0, 0);
;       RESC(alB); __syncthreads();
;       SBAR(); at_qkt(pA0, pA1, K_lds, qr, r32, hi, -m_reg);
;       at_finishSM(pB0, pB1, alB, l_reg, pa0, pa1, pa2, pa3); SBAR();
;       if (j + 3 < NT) SLOAD(0, (j + 3) * 64); SBAR();
;       pv_d0(o, vb0 + AT_SHMV, pa0, pa1, pa2, pa3); at_partialSM(pA0, pA1, m_reg, alA, false);
;       __syncthreads(); SWAIT(); SWRITE(1, 1);
;       RESC(alA); __syncthreads();
.Lat_rare0_back:
	v_add_f32_e32 v173, v173, v175
	v_cvt_pk_bf16_f32 v104, v32, v33
	v_cvt_pk_bf16_f32 v105, v34, v35
	v_cvt_pk_bf16_f32 v106, v36, v37
	v_cvt_pk_bf16_f32 v107, v38, v39
	v_cvt_pk_bf16_f32 v108, v40, v41
	v_cvt_pk_bf16_f32 v109, v42, v43
	v_cvt_pk_bf16_f32 v110, v44, v45
	v_cvt_pk_bf16_f32 v111, v46, v47
	v_cvt_pk_bf16_f32 v112, v48, v49
	v_cvt_pk_bf16_f32 v113, v50, v51
	v_cvt_pk_bf16_f32 v114, v52, v53
	v_cvt_pk_bf16_f32 v115, v54, v55
	v_cvt_pk_bf16_f32 v116, v56, v57
	v_cvt_pk_bf16_f32 v117, v58, v59
	v_cvt_pk_bf16_f32 v118, v60, v61
	v_cvt_pk_bf16_f32 v119, v62, v63
	ds_read_b128 v[184:187], v170 offset:26624
	ds_read_b128 v[188:191], v170 offset:33280
	ds_read_b128 v[192:195], v170 offset:26656
	ds_read_b128 v[196:199], v170 offset:33312
	s_barrier
	ds_read_b128 v[200:203], v170 offset:26688
	ds_read_b128 v[204:207], v170 offset:33344
	s_waitcnt lgkmcnt(4)
	v_mfma_f32_32x32x16_bf16 v[32:47], v[184:187], v[80:83], v[64:79]
	v_mfma_f32_32x32x16_bf16 v[48:63], v[188:191], v[80:83], v[64:79]
	ds_read_b128 v[208:211], v170 offset:26720
	ds_read_b128 v[212:215], v170 offset:33376
	s_waitcnt lgkmcnt(4)
	v_mfma_f32_32x32x16_bf16 v[32:47], v[192:195], v[84:87], v[32:47]
	v_mfma_f32_32x32x16_bf16 v[48:63], v[196:199], v[84:87], v[48:63]
	ds_read_b128 v[184:187], v170 offset:26752
	ds_read_b128 v[188:191], v170 offset:33408
	s_waitcnt lgkmcnt(4)
	v_mfma_f32_32x32x16_bf16 v[32:47], v[200:203], v[88:91], v[32:47]
	v_mfma_f32_32x32x16_bf16 v[48:63], v[204:207], v[88:91], v[48:63]
	ds_read_b128 v[192:195], v170 offset:26784
	ds_read_b128 v[196:199], v170 offset:33440
	s_waitcnt lgkmcnt(4)
	v_mfma_f32_32x32x16_bf16 v[32:47], v[208:211], v[92:95], v[32:47]
	v_mfma_f32_32x32x16_bf16 v[48:63], v[212:215], v[92:95], v[48:63]
	ds_read_b64_tr_b16 v[148:149], v171 offset:16384
	ds_read_b64_tr_b16 v[150:151], v171 offset:18432
	ds_read_b64_tr_b16 v[152:153], v171 offset:20480
	ds_read_b64_tr_b16 v[154:155], v171 offset:22528
	s_waitcnt lgkmcnt(6)
	v_mfma_f32_32x32x16_bf16 v[32:47], v[184:187], v[96:99], v[32:47]
	v_mfma_f32_32x32x16_bf16 v[48:63], v[188:191], v[96:99], v[48:63]
	ds_read_b64_tr_b16 v[156:157], v171 offset:24576
	ds_read_b64_tr_b16 v[158:159], v171 offset:26624
	ds_read_b64_tr_b16 v[216:217], v171 offset:28672
	ds_read_b64_tr_b16 v[218:219], v171 offset:30720
	s_waitcnt lgkmcnt(8)
	v_mfma_f32_32x32x16_bf16 v[32:47], v[192:195], v[100:103], v[32:47]
	v_mfma_f32_32x32x16_bf16 v[48:63], v[196:199], v[100:103], v[48:63]
	ds_read_b64_tr_b16 v[220:221], v171 offset:16896
	ds_read_b64_tr_b16 v[222:223], v171 offset:18944
	ds_read_b64_tr_b16 v[224:225], v171 offset:20992
	ds_read_b64_tr_b16 v[226:227], v171 offset:23040
	s_waitcnt lgkmcnt(10)
	v_mfma_f32_32x32x16_bf16 v[0:15], v[104:107], v[148:151], v[0:15]
	s_waitcnt lgkmcnt(8)
	v_mfma_f32_32x32x16_bf16 v[0:15], v[108:111], v[152:155], v[0:15]
	ds_read_b64_tr_b16 v[236:237], v171 offset:25088
	ds_read_b64_tr_b16 v[238:239], v171 offset:27136
	ds_read_b64_tr_b16 v[240:241], v171 offset:29184
	ds_read_b64_tr_b16 v[242:243], v171 offset:31232
	s_waitcnt lgkmcnt(10)
	v_mfma_f32_32x32x16_bf16 v[0:15], v[112:115], v[156:159], v[0:15]
	s_waitcnt lgkmcnt(8)
	v_mfma_f32_32x32x16_bf16 v[0:15], v[116:119], v[216:219], v[0:15]
	s_waitcnt lgkmcnt(6)
	v_mfma_f32_32x32x16_bf16 v[16:31], v[104:107], v[220:223], v[16:31]
	s_waitcnt lgkmcnt(4)
	v_mfma_f32_32x32x16_bf16 v[16:31], v[108:111], v[224:227], v[16:31]
	s_waitcnt lgkmcnt(2)
	v_mfma_f32_32x32x16_bf16 v[16:31], v[112:115], v[236:239], v[16:31]
	s_waitcnt lgkmcnt(0)
	v_mfma_f32_32x32x16_bf16 v[16:31], v[116:119], v[240:243], v[16:31]
	s_barrier
	s_waitcnt vmcnt(3)
	ds_write_b128 v167, v[120:123] offset:0
	ds_write_b128 v131, v[124:127] offset:0
	ds_write_b128 v169, v[132:135] offset:0
	v_exp_f32_e32 v32, v32
	v_exp_f32_e32 v48, v48
	v_exp_f32_e32 v33, v33
	v_exp_f32_e32 v49, v49
	v_exp_f32_e32 v34, v34
	v_exp_f32_e32 v50, v50
	v_exp_f32_e32 v35, v35
	v_exp_f32_e32 v51, v51
	v_exp_f32_e32 v36, v36
	v_exp_f32_e32 v52, v52
	v_exp_f32_e32 v37, v37
	v_exp_f32_e32 v53, v53
	v_exp_f32_e32 v38, v38
	v_exp_f32_e32 v54, v54
	v_exp_f32_e32 v39, v39
	v_exp_f32_e32 v55, v55
	v_exp_f32_e32 v40, v40
	v_exp_f32_e32 v56, v56
	v_exp_f32_e32 v41, v41
	v_exp_f32_e32 v57, v57
	v_exp_f32_e32 v42, v42
	v_exp_f32_e32 v58, v58
	v_exp_f32_e32 v43, v43
	v_exp_f32_e32 v59, v59
	v_exp_f32_e32 v44, v44
	v_exp_f32_e32 v60, v60
	v_exp_f32_e32 v45, v45
	v_exp_f32_e32 v61, v61
	v_exp_f32_e32 v46, v46
	v_exp_f32_e32 v62, v62
	v_exp_f32_e32 v47, v47
	v_exp_f32_e32 v63, v63
	s_waitcnt lgkmcnt(0)
	global_load_dwordx4 v[120:123], v129, s[4:5]
	global_load_dwordx4 v[124:127], v129, s[4:5] offset:128
	global_load_dwordx4 v[132:135], v130, s[6:7]
	s_add_u32 s4, s4, 0x40000
	s_addc_u32 s5, s5, 0
	s_add_u32 s6, s6, 0x1000
	s_addc_u32 s7, s7, 0
	v_add_f32_e32 v175, v32, v33
	v_add_f32_e32 v174, v48, v49
	v_add_f32_e32 v175, v175, v34
	v_add_f32_e32 v174, v174, v50
	v_add_f32_e32 v175, v175, v35
	v_add_f32_e32 v174, v174, v51
	v_add_f32_e32 v175, v175, v36
	v_add_f32_e32 v174, v174, v52
	v_add_f32_e32 v175, v175, v37
	v_add_f32_e32 v174, v174, v53
	v_add_f32_e32 v175, v175, v38
	v_add_f32_e32 v174, v174, v54
	v_add_f32_e32 v175, v175, v39
	v_add_f32_e32 v174, v174, v55
	v_add_f32_e32 v175, v175, v40
	v_add_f32_e32 v174, v174, v56
	v_add_f32_e32 v175, v175, v41
	v_add_f32_e32 v174, v174, v57
	v_add_f32_e32 v175, v175, v42
	v_add_f32_e32 v174, v174, v58
	v_add_f32_e32 v175, v175, v43
	v_add_f32_e32 v174, v174, v59
	v_add_f32_e32 v175, v175, v44
	v_add_f32_e32 v174, v174, v60
	v_add_f32_e32 v175, v175, v45
	v_add_f32_e32 v174, v174, v61
	v_add_f32_e32 v175, v175, v46
	v_add_f32_e32 v174, v174, v62
	v_add_f32_e32 v175, v175, v47
	v_add_f32_e32 v174, v174, v63
	v_add_f32_e32 v175, v175, v174
	v_cmp_ge_f32_e32 vcc, s23, v175
	s_cmp_eq_u64 vcc, exec
	s_cbranch_scc0 .Lat_rare1
; __device__ __forceinline__ void at_finishSM(f32x16& p0, f32x16& p1, float alpha, float& l_reg, bf16x8& pa0, bf16x8& pa1, bf16x8& pa2, bf16x8& pa3) {
; #pragma unroll
;   for (int r = 0; r < 16; ++r) p1[r] = __builtin_amdgcn_exp2f(p1[r]);
;   float ps = 0;
; #pragma unroll
;   for (int r = 0; r < 16; ++r) ps += p0[r];
; #pragma unroll
;   for (int r = 0; r < 16; ++r) ps += p1[r];
;   { auto rr = __builtin_amdgcn_permlane32_swap(__float_as_uint(ps), __float_as_uint(ps), false, false);
;     ps = __uint_as_float(rr[0]) + __uint_as_float(rr[1]); }
;   l_reg = l_reg * alpha + ps;
;     ...
;   PK4(p0, 0, pa0); PK4(p0, 8, pa1); PK4(p1, 0, pa2); PK4(p1, 8, pa3);
;     ...
; }
; __device__ __forceinline__ void at_qkt(f32x16& p0, f32x16& p1, const char* Ks, const bf16x8* qr, int r32, int hi, float negm) {
; #pragma unroll
;   for (int r = 0; r < 16; ++r) { p0[r] = negm; p1[r] = negm; }
; #pragma unroll
;   for (int d0 = 0; d0 < 6; ++d0) {
;     const bf16x8 b0 = *(const bf16x8*)(Ks + r32 * AT_KROW + d0 * 32 + hi * 16);
;     const bf16x8 b1 = *(const bf16x8*)(Ks + (32 + r32) * AT_KROW + d0 * 32 + hi * 16);
;     p0 = MFMA(b0, qr[d0], p0);
;     p1 = MFMA(b1, qr[d0], p1);
;   }
; }
; __device__ __forceinline__ int v_st(int k, int c) { const int kk = (k & ~0xC) | ((k & 4) << 1) | ((k & 8) >> 1); return ((kk >> 3) * 4 + (c >> 5)) * 512 + ((kk & 7) * 32 + (c & 31)) * 2; }
; __device__ __forceinline__ int v_rd_base(int lane) { return ((lane & 3) << 3) | (((lane >> 2) & 3) << 6) | (((lane >> 4) & 1) << 5) | (((lane >> 5) & 1) << 8); }
; __device__ void phase_attn(const Params& p, char* lds) {
;     ...
;     for (int j = 1; j + 1 < NT; j += 2) {
;       SBAR(); at_qkt(pB0, pB1, K_lds + AT_SHMK, qr, r32, hi, -m_reg);
;       at_finishSM(pA0, pA1, alA, l_reg, pa0, pa1, pa2, pa3); SBAR();
;       SLOAD(1, (j + 2) * 64); SBAR();
;       pv_d0(o, vb0, pa0, pa1, pa2, pa3); at_partialSM(pB0, pB1, m_reg, alB, false);
;       __syncthreads(); SWAIT(); SWRITE(0, 0);
;       RESC(alB); __syncthreads();
;       SBAR(); at_qkt(pA0, pA1, K_lds, qr, r32, hi, -m_reg);
;       at_finishSM(pB0, pB1, alB, l_reg, pa0, pa1, pa2, pa3); SBAR();
;       if (j + 3 < NT) SLOAD(0, (j + 3) * 64); SBAR();
;       pv_d0(o, vb0 + AT_SHMV, pa0, pa1, pa2, pa3); at_partialSM(pA0, pA1, m_reg, alA, false);
;       __syncthreads(); SWAIT(); SWRITE(1, 1);
;       RESC(alA); __syncthreads();
.Lat_rare1_back:
	v_add_f32_e32 v173, v173, v175
	v_cvt_pk_bf16_f32 v104, v32, v33
	v_cvt_pk_bf16_f32 v105, v34, v35
	v_cvt_pk_bf16_f32 v106, v36, v37
	v_cvt_pk_bf16_f32 v107, v38, v39
	v_cvt_pk_bf16_f32 v108, v40, v41
	v_cvt_pk_bf16_f32 v109, v42, v43
	v_cvt_pk_bf16_f32 v110, v44, v45
	v_cvt_pk_bf16_f32 v111, v46, v47
	v_cvt_pk_bf16_f32 v112, v48, v49
	v_cvt_pk_bf16_f32 v113, v50, v51
	v_cvt_pk_bf16_f32 v114, v52, v53
	v_cvt_pk_bf16_f32 v115, v54, v55
	v_cvt_pk_bf16_f32 v116, v56, v57
	v_cvt_pk_bf16_f32 v117, v58, v59
	v_cvt_pk_bf16_f32 v118, v60, v61
	v_cvt_pk_bf16_f32 v119, v62, v63
	ds_read_b128 v[184:187], v170 offset:39936
	ds_read_b128 v[188:191], v170 offset:46592
	ds_read_b128 v[192:195], v170 offset:39968
	ds_read_b128 v[196:199], v170 offset:46624
	s_barrier
	ds_read_b128 v[200:203], v170 offset:40000
	ds_read_b128 v[204:207], v170 offset:46656
	s_waitcnt lgkmcnt(4)
	v_mfma_f32_32x32x16_bf16 v[32:47], v[184:187], v[80:83], v[64:79]
	v_mfma_f32_32x32x16_bf16 v[48:63], v[188:191], v[80:83], v[64:79]
	ds_read_b128 v[208:211], v170 offset:40032
	ds_read_b128 v[212:215], v170 offset:46688
	s_waitcnt lgkmcnt(4)
	v_mfma_f32_32x32x16_bf16 v[32:47], v[192:195], v[84:87], v[32:47]
	v_mfma_f32_32x32x16_bf16 v[48:63], v[196:199], v[84:87], v[48:63]
	ds_read_b128 v[184:187], v170 offset:40064
	ds_read_b128 v[188:191], v170 offset:46720
	s_waitcnt lgkmcnt(4)
	v_mfma_f32_32x32x16_bf16 v[32:47], v[200:203], v[88:91], v[32:47]
	v_mfma_f32_32x32x16_bf16 v[48:63], v[204:207], v[88:91], v[48:63]
	ds_read_b128 v[192:195], v170 offset:40096
	ds_read_b128 v[196:199], v170 offset:46752
	s_waitcnt lgkmcnt(4)
	v_mfma_f32_32x32x16_bf16 v[32:47], v[208:211], v[92:95], v[32:47]
	v_mfma_f32_32x32x16_bf16 v[48:63], v[212:215], v[92:95], v[48:63]
	ds_read_b64_tr_b16 v[148:149], v171 offset:32768
	ds_read_b64_tr_b16 v[150:151], v171 offset:34816
	ds_read_b64_tr_b16 v[152:153], v171 offset:36864
	ds_read_b64_tr_b16 v[154:155], v171 offset:38912
	s_waitcnt lgkmcnt(6)
	v_mfma_f32_32x32x16_bf16 v[32:47], v[184:187], v[96:99], v[32:47]
	v_mfma_f32_32x32x16_bf16 v[48:63], v[188:191], v[96:99], v[48:63]
	ds_read_b64_tr_b16 v[156:157], v171 offset:40960
	ds_read_b64_tr_b16 v[158:159], v171 offset:43008
	ds_read_b64_tr_b16 v[216:217], v171 offset:45056
	ds_read_b64_tr_b16 v[218:219], v171 offset:47104
	s_waitcnt lgkmcnt(8)
	v_mfma_f32_32x32x16_bf16 v[32:47], v[192:195], v[100:103], v[32:47]
	v_mfma_f32_32x32x16_bf16 v[48:63], v[196:199], v[100:103], v[48:63]
	ds_read_b64_tr_b16 v[220:221], v171 offset:33280
	ds_read_b64_tr_b16 v[222:223], v171 offset:35328
	ds_read_b64_tr_b16 v[224:225], v171 offset:37376
	ds_read_b64_tr_b16 v[226:227], v171 offset:39424
	s_waitcnt lgkmcnt(10)
	v_mfma_f32_32x32x16_bf16 v[0:15], v[104:107], v[148:151], v[0:15]
	s_waitcnt lgkmcnt(8)
	v_mfma_f32_32x32x16_bf16 v[0:15], v[108:111], v[152:155], v[0:15]
	ds_read_b64_tr_b16 v[236:237], v171 offset:41472
	ds_read_b64_tr_b16 v[238:239], v171 offset:43520
	ds_read_b64_tr_b16 v[240:241], v171 offset:45568
	ds_read_b64_tr_b16 v[242:243], v171 offset:47616
	s_waitcnt lgkmcnt(10)
	v_mfma_f32_32x32x16_bf16 v[0:15], v[112:115], v[156:159], v[0:15]
	s_waitcnt lgkmcnt(8)
	v_mfma_f32_32x32x16_bf16 v[0:15], v[116:119], v[216:219], v[0:15]
	s_waitcnt lgkmcnt(6)
	v_mfma_f32_32x32x16_bf16 v[16:31], v[104:107], v[220:223], v[16:31]
	s_waitcnt lgkmcnt(4)
	v_mfma_f32_32x32x16_bf16 v[16:31], v[108:111], v[224:227], v[16:31]
	s_waitcnt lgkmcnt(2)
	v_mfma_f32_32x32x16_bf16 v[16:31], v[112:115], v[236:239], v[16:31]
	s_waitcnt lgkmcnt(0)
	v_mfma_f32_32x32x16_bf16 v[16:31], v[116:119], v[240:243], v[16:31]
	s_barrier
	s_waitcnt vmcnt(3)
	ds_write_b128 v167, v[136:139] offset:13312
	ds_write_b128 v131, v[140:143] offset:16384
	ds_write_b128 v169, v[144:147] offset:13312
	v_exp_f32_e32 v32, v32
	v_exp_f32_e32 v48, v48
	v_exp_f32_e32 v33, v33
	v_exp_f32_e32 v49, v49
	v_exp_f32_e32 v34, v34
	v_exp_f32_e32 v50, v50
	v_exp_f32_e32 v35, v35
	v_exp_f32_e32 v51, v51
	v_exp_f32_e32 v36, v36
	v_exp_f32_e32 v52, v52
	v_exp_f32_e32 v37, v37
	v_exp_f32_e32 v53, v53
	v_exp_f32_e32 v38, v38
	v_exp_f32_e32 v54, v54
	v_exp_f32_e32 v39, v39
	v_exp_f32_e32 v55, v55
	v_exp_f32_e32 v40, v40
	v_exp_f32_e32 v56, v56
	v_exp_f32_e32 v41, v41
	v_exp_f32_e32 v57, v57
	v_exp_f32_e32 v42, v42
	v_exp_f32_e32 v58, v58
	v_exp_f32_e32 v43, v43
	v_exp_f32_e32 v59, v59
	v_exp_f32_e32 v44, v44
	v_exp_f32_e32 v60, v60
	v_exp_f32_e32 v45, v45
	v_exp_f32_e32 v61, v61
	v_exp_f32_e32 v46, v46
	v_exp_f32_e32 v62, v62
	v_exp_f32_e32 v47, v47
	v_exp_f32_e32 v63, v63
	s_waitcnt lgkmcnt(0)
	global_load_dwordx4 v[136:139], v129, s[4:5]
	global_load_dwordx4 v[140:143], v129, s[4:5] offset:128
	global_load_dwordx4 v[144:147], v130, s[6:7]
	s_add_u32 s4, s4, 0x40000
	s_addc_u32 s5, s5, 0
	s_add_u32 s6, s6, 0x1000
	s_addc_u32 s7, s7, 0
	v_add_f32_e32 v175, v32, v33
	v_add_f32_e32 v174, v48, v49
	v_add_f32_e32 v175, v175, v34
	v_add_f32_e32 v174, v174, v50
	v_add_f32_e32 v175, v175, v35
	v_add_f32_e32 v174, v174, v51
	v_add_f32_e32 v175, v175, v36
	v_add_f32_e32 v174, v174, v52
	v_add_f32_e32 v175, v175, v37
	v_add_f32_e32 v174, v174, v53
	v_add_f32_e32 v175, v175, v38
	v_add_f32_e32 v174, v174, v54
	v_add_f32_e32 v175, v175, v39
	v_add_f32_e32 v174, v174, v55
	v_add_f32_e32 v175, v175, v40
	v_add_f32_e32 v174, v174, v56
	v_add_f32_e32 v175, v175, v41
	v_add_f32_e32 v174, v174, v57
	v_add_f32_e32 v175, v175, v42
	v_add_f32_e32 v174, v174, v58
	v_add_f32_e32 v175, v175, v43
	v_add_f32_e32 v174, v174, v59
	v_add_f32_e32 v175, v175, v44
	v_add_f32_e32 v174, v174, v60
	v_add_f32_e32 v175, v175, v45
	v_add_f32_e32 v174, v174, v61
	v_add_f32_e32 v175, v175, v46
	v_add_f32_e32 v174, v174, v62
	v_add_f32_e32 v175, v175, v47
	v_add_f32_e32 v174, v174, v63
	v_add_f32_e32 v175, v175, v174
	v_cmp_ge_f32_e32 vcc, s23, v175
	s_cmp_eq_u64 vcc, exec
	s_cbranch_scc0 .Lat_rare2
; __device__ __forceinline__ void at_finishSM(f32x16& p0, f32x16& p1, float alpha, float& l_reg, bf16x8& pa0, bf16x8& pa1, bf16x8& pa2, bf16x8& pa3) {
; #pragma unroll
;   for (int r = 0; r < 16; ++r) p1[r] = __builtin_amdgcn_exp2f(p1[r]);
;   float ps = 0;
; #pragma unroll
;   for (int r = 0; r < 16; ++r) ps += p0[r];
; #pragma unroll
;   for (int r = 0; r < 16; ++r) ps += p1[r];
;   { auto rr = __builtin_amdgcn_permlane32_swap(__float_as_uint(ps), __float_as_uint(ps), false, false);
;     ps = __uint_as_float(rr[0]) + __uint_as_float(rr[1]); }
;   l_reg = l_reg * alpha + ps;
;     ...
;   PK4(p0, 0, pa0); PK4(p0, 8, pa1); PK4(p1, 0, pa2); PK4(p1, 8, pa3);
;     ...
; }
; __device__ __forceinline__ void at_qkt(f32x16& p0, f32x16& p1, const char* Ks, const bf16x8* qr, int r32, int hi, float negm) {
; #pragma unroll
;   for (int r = 0; r < 16; ++r) { p0[r] = negm; p1[r] = negm; }
; #pragma unroll
;   for (int d0 = 0; d0 < 6; ++d0) {
;     const bf16x8 b0 = *(const bf16x8*)(Ks + r32 * AT_KROW + d0 * 32 + hi * 16);
;     const bf16x8 b1 = *(const bf16x8*)(Ks + (32 + r32) * AT_KROW + d0 * 32 + hi * 16);
;     p0 = MFMA(b0, qr[d0], p0);
;     p1 = MFMA(b1, qr[d0], p1);
;   }
; }
; __device__ __forceinline__ int v_st(int k, int c) { const int kk = (k & ~0xC) | ((k & 4) << 1) | ((k & 8) >> 1); return ((kk >> 3) * 4 + (c >> 5)) * 512 + ((kk & 7) * 32 + (c & 31)) * 2; }
; __device__ __forceinline__ int v_rd_base(int lane) { return ((lane & 3) << 3) | (((lane >> 2) & 3) << 6) | (((lane >> 4) & 1) << 5) | (((lane >> 5) & 1) << 8); }
; __device__ void phase_attn(const Params& p, char* lds) {
;     ...
;     for (int j = 1; j + 1 < NT; j += 2) {
;       SBAR(); at_qkt(pB0, pB1, K_lds + AT_SHMK, qr, r32, hi, -m_reg);
;       at_finishSM(pA0, pA1, alA, l_reg, pa0, pa1, pa2, pa3); SBAR();
;       SLOAD(1, (j + 2) * 64); SBAR();
;       pv_d0(o, vb0, pa0, pa1, pa2, pa3); at_partialSM(pB0, pB1, m_reg, alB, false);
;       __syncthreads(); SWAIT(); SWRITE(0, 0);
;       RESC(alB); __syncthreads();
;       SBAR(); at_qkt(pA0, pA1, K_lds, qr, r32, hi, -m_reg);
;       at_finishSM(pB0, pB1, alB, l_reg, pa0, pa1, pa2, pa3); SBAR();
;       if (j + 3 < NT) SLOAD(0, (j + 3) * 64); SBAR();
;       pv_d0(o, vb0 + AT_SHMV, pa0, pa1, pa2, pa3); at_partialSM(pA0, pA1, m_reg, alA, false);
;       __syncthreads(); SWAIT(); SWRITE(1, 1);
;       RESC(alA); __syncthreads();
.Lat_rare2_back:
	v_add_f32_e32 v173, v173, v175
	v_cvt_pk_bf16_f32 v104, v32, v33
	v_cvt_pk_bf16_f32 v105, v34, v35
	v_cvt_pk_bf16_f32 v106, v36, v37
	v_cvt_pk_bf16_f32 v107, v38, v39
	v_cvt_pk_bf16_f32 v108, v40, v41
	v_cvt_pk_bf16_f32 v109, v42, v43
	v_cvt_pk_bf16_f32 v110, v44, v45
	v_cvt_pk_bf16_f32 v111, v46, v47
	v_cvt_pk_bf16_f32 v112, v48, v49
	v_cvt_pk_bf16_f32 v113, v50, v51
	v_cvt_pk_bf16_f32 v114, v52, v53
	v_cvt_pk_bf16_f32 v115, v54, v55
	v_cvt_pk_bf16_f32 v116, v56, v57
	v_cvt_pk_bf16_f32 v117, v58, v59
	v_cvt_pk_bf16_f32 v118, v60, v61
	v_cvt_pk_bf16_f32 v119, v62, v63
	ds_read_b128 v[184:187], v170 offset:0
	ds_read_b128 v[188:191], v170 offset:6656
	ds_read_b128 v[192:195], v170 offset:32
	ds_read_b128 v[196:199], v170 offset:6688
	s_barrier
	ds_read_b128 v[200:203], v170 offset:64
	ds_read_b128 v[204:207], v170 offset:6720
	s_waitcnt lgkmcnt(4)
	v_mfma_f32_32x32x16_bf16 v[32:47], v[184:187], v[80:83], v[64:79]
	v_mfma_f32_32x32x16_bf16 v[48:63], v[188:191], v[80:83], v[64:79]
	ds_read_b128 v[208:211], v170 offset:96
	ds_read_b128 v[212:215], v170 offset:6752
	s_waitcnt lgkmcnt(4)
	v_mfma_f32_32x32x16_bf16 v[32:47], v[192:195], v[84:87], v[32:47]
	v_mfma_f32_32x32x16_bf16 v[48:63], v[196:199], v[84:87], v[48:63]
	ds_read_b128 v[184:187], v170 offset:128
	ds_read_b128 v[188:191], v170 offset:6784
	s_waitcnt lgkmcnt(4)
	v_mfma_f32_32x32x16_bf16 v[32:47], v[200:203], v[88:91], v[32:47]
	v_mfma_f32_32x32x16_bf16 v[48:63], v[204:207], v[88:91], v[48:63]
	ds_read_b128 v[192:195], v170 offset:160
	ds_read_b128 v[196:199], v170 offset:6816
	s_waitcnt lgkmcnt(4)
	v_mfma_f32_32x32x16_bf16 v[32:47], v[208:211], v[92:95], v[32:47]
	v_mfma_f32_32x32x16_bf16 v[48:63], v[212:215], v[92:95], v[48:63]
	ds_read_b64_tr_b16 v[148:149], v171 offset:49152
	ds_read_b64_tr_b16 v[150:151], v171 offset:51200
	ds_read_b64_tr_b16 v[152:153], v171 offset:53248
	ds_read_b64_tr_b16 v[154:155], v171 offset:55296
	s_waitcnt lgkmcnt(6)
	v_mfma_f32_32x32x16_bf16 v[32:47], v[184:187], v[96:99], v[32:47]
	v_mfma_f32_32x32x16_bf16 v[48:63], v[188:191], v[96:99], v[48:63]
	ds_read_b64_tr_b16 v[156:157], v171 offset:57344
	ds_read_b64_tr_b16 v[158:159], v171 offset:59392
	ds_read_b64_tr_b16 v[216:217], v171 offset:61440
	ds_read_b64_tr_b16 v[218:219], v171 offset:63488
	s_waitcnt lgkmcnt(8)
	v_mfma_f32_32x32x16_bf16 v[32:47], v[192:195], v[100:103], v[32:47]
	v_mfma_f32_32x32x16_bf16 v[48:63], v[196:199], v[100:103], v[48:63]
	ds_read_b64_tr_b16 v[220:221], v171 offset:49664
	ds_read_b64_tr_b16 v[222:223], v171 offset:51712
	ds_read_b64_tr_b16 v[224:225], v171 offset:53760
	ds_read_b64_tr_b16 v[226:227], v171 offset:55808
	s_waitcnt lgkmcnt(10)
	v_mfma_f32_32x32x16_bf16 v[0:15], v[104:107], v[148:151], v[0:15]
	s_waitcnt lgkmcnt(8)
	v_mfma_f32_32x32x16_bf16 v[0:15], v[108:111], v[152:155], v[0:15]
	ds_read_b64_tr_b16 v[236:237], v171 offset:57856
	ds_read_b64_tr_b16 v[238:239], v171 offset:59904
	ds_read_b64_tr_b16 v[240:241], v171 offset:61952
	ds_read_b64_tr_b16 v[242:243], v171 offset:64000
	s_waitcnt lgkmcnt(10)
	v_mfma_f32_32x32x16_bf16 v[0:15], v[112:115], v[156:159], v[0:15]
	s_waitcnt lgkmcnt(8)
	v_mfma_f32_32x32x16_bf16 v[0:15], v[116:119], v[216:219], v[0:15]
	s_waitcnt lgkmcnt(6)
	v_mfma_f32_32x32x16_bf16 v[16:31], v[104:107], v[220:223], v[16:31]
	s_waitcnt lgkmcnt(4)
	v_mfma_f32_32x32x16_bf16 v[16:31], v[108:111], v[224:227], v[16:31]
	s_waitcnt lgkmcnt(2)
	v_mfma_f32_32x32x16_bf16 v[16:31], v[112:115], v[236:239], v[16:31]
	s_waitcnt lgkmcnt(0)
	v_mfma_f32_32x32x16_bf16 v[16:31], v[116:119], v[240:243], v[16:31]
	s_barrier
	s_waitcnt vmcnt(3)
	ds_write_b128 v167, v[120:123] offset:26624
	ds_write_b128 v131, v[124:127] offset:32768
	ds_write_b128 v169, v[132:135] offset:26624
	v_exp_f32_e32 v32, v32
	v_exp_f32_e32 v48, v48
	v_exp_f32_e32 v33, v33
	v_exp_f32_e32 v49, v49
	v_exp_f32_e32 v34, v34
	v_exp_f32_e32 v50, v50
	v_exp_f32_e32 v35, v35
	v_exp_f32_e32 v51, v51
	v_exp_f32_e32 v36, v36
	v_exp_f32_e32 v52, v52
	v_exp_f32_e32 v37, v37
	v_exp_f32_e32 v53, v53
	v_exp_f32_e32 v38, v38
	v_exp_f32_e32 v54, v54
	v_exp_f32_e32 v39, v39
	v_exp_f32_e32 v55, v55
	v_exp_f32_e32 v40, v40
	v_exp_f32_e32 v56, v56
	v_exp_f32_e32 v41, v41
	v_exp_f32_e32 v57, v57
	v_exp_f32_e32 v42, v42
	v_exp_f32_e32 v58, v58
	v_exp_f32_e32 v43, v43
	v_exp_f32_e32 v59, v59
	v_exp_f32_e32 v44, v44
	v_exp_f32_e32 v60, v60
	v_exp_f32_e32 v45, v45
	v_exp_f32_e32 v61, v61
	v_exp_f32_e32 v46, v46
	v_exp_f32_e32 v62, v62
	v_exp_f32_e32 v47, v47
	v_exp_f32_e32 v63, v63
	s_waitcnt lgkmcnt(0)
	global_load_dwordx4 v[120:123], v129, s[4:5]
	global_load_dwordx4 v[124:127], v129, s[4:5] offset:128
	global_load_dwordx4 v[132:135], v130, s[6:7]
	s_add_u32 s4, s4, 0x40000
	s_addc_u32 s5, s5, 0
	s_add_u32 s6, s6, 0x1000
	s_addc_u32 s7, s7, 0
	v_add_f32_e32 v175, v32, v33
	v_add_f32_e32 v174, v48, v49
	v_add_f32_e32 v175, v175, v34
	v_add_f32_e32 v174, v174, v50
	v_add_f32_e32 v175, v175, v35
	v_add_f32_e32 v174, v174, v51
	v_add_f32_e32 v175, v175, v36
	v_add_f32_e32 v174, v174, v52
	v_add_f32_e32 v175, v175, v37
	v_add_f32_e32 v174, v174, v53
	v_add_f32_e32 v175, v175, v38
	v_add_f32_e32 v174, v174, v54
	v_add_f32_e32 v175, v175, v39
	v_add_f32_e32 v174, v174, v55
	v_add_f32_e32 v175, v175, v40
	v_add_f32_e32 v174, v174, v56
	v_add_f32_e32 v175, v175, v41
	v_add_f32_e32 v174, v174, v57
	v_add_f32_e32 v175, v175, v42
	v_add_f32_e32 v174, v174, v58
	v_add_f32_e32 v175, v175, v43
	v_add_f32_e32 v174, v174, v59
	v_add_f32_e32 v175, v175, v44
	v_add_f32_e32 v174, v174, v60
	v_add_f32_e32 v175, v175, v45
	v_add_f32_e32 v174, v174, v61
	v_add_f32_e32 v175, v175, v46
	v_add_f32_e32 v174, v174, v62
	v_add_f32_e32 v175, v175, v47
	v_add_f32_e32 v174, v174, v63
	v_add_f32_e32 v175, v175, v174
	v_cmp_ge_f32_e32 vcc, s23, v175
	s_cmp_eq_u64 vcc, exec
	s_cbranch_scc0 .Lat_rare3
; #define SBAR() __builtin_amdgcn_sched_barrier(0)
; #define SLOAD(i, k0) do { sr_[i].vs = *(const bf16x8*)(Kh + (size_t)((k0) + skey) * 2048 + 64 + sc8); \
;     sr_[i].ks = *(const bf16x8*)(Kh + (size_t)((k0) + skey) * 2048 + sc8); \
;     sr_[i].ps = *(const bf16x8*)(Kp + (size_t)((k0) + pkey) * 32 + pc8); } while (0)
; #define SWRITE(bb, i) do { *(bf16x8*)(V_lds + (bb) * AT_SHMV + vst) = sr_[i].vs; \
;     *(bf16x8*)(K_lds + (bb) * AT_SHMK + kst) = sr_[i].ks; \
;     *(bf16x8*)(K_lds + (bb) * AT_SHMK + pst) = sr_[i].ps; } while (0)
; #define SWAIT() asm volatile("s_waitcnt vmcnt(3)" ::: "memory")
; #define RESC(a) do { if (__any((a) < 1.f)) { if (hi == 0) al_l[r32] = (a); asm volatile("s_waitcnt lgkmcnt(0)" ::: "memory"); \
;     _Pragma("unroll") for (int dd = 0; dd < 2; ++dd) _Pragma("unroll") for (int r = 0; r < 16; ++r) o[dd][r] *= al_l[crow(r, hi)]; } } while (0)
; __device__ void phase_attn(const Params& p, char* lds) {
;     ...
;     for (int j = 1; j + 1 < NT; j += 2) {
;       SBAR(); at_qkt(pB0, pB1, K_lds + AT_SHMK, qr, r32, hi, -m_reg);
;       at_finishSM(pA0, pA1, alA, l_reg, pa0, pa1, pa2, pa3); SBAR();
;       SLOAD(1, (j + 2) * 64); SBAR();
;       pv_d0(o, vb0, pa0, pa1, pa2, pa3); at_partialSM(pB0, pB1, m_reg, alB, false);
;       __syncthreads(); SWAIT(); SWRITE(0, 0);
;       RESC(alB); __syncthreads();
;       SBAR(); at_qkt(pA0, pA1, K_lds, qr, r32, hi, -m_reg);
;       at_finishSM(pB0, pB1, alB, l_reg, pa0, pa1, pa2, pa3); SBAR();
;       if (j + 3 < NT) SLOAD(0, (j + 3) * 64); SBAR();
;       pv_d0(o, vb0 + AT_SHMV, pa0, pa1, pa2, pa3); at_partialSM(pA0, pA1, m_reg, alA, false);
;       __syncthreads(); SWAIT(); SWRITE(1, 1);
;       RESC(alA); __syncthreads();
;     }
;     SBAR(); at_qkt(pB0, pB1, K_lds + AT_SHMK, qr, r32, hi, -m_reg);
;     at_finishSM(pA0, pA1, alA, l_reg, pa0, pa1, pa2, pa3); SBAR();
;     pv_d0(o, vb0, pa0, pa1, pa2, pa3); at_partialSM(pB0, pB1, m_reg, alB, false);
;     __syncthreads(); RESC(alB);
;     at_finishSM(pB0, pB1, alB, l_reg, pa0, pa1, pa2, pa3); SBAR();
.Lat_rare3_back:
	v_add_f32_e32 v173, v173, v175
	v_cvt_pk_bf16_f32 v104, v32, v33
	v_cvt_pk_bf16_f32 v105, v34, v35
	v_cvt_pk_bf16_f32 v106, v36, v37
	v_cvt_pk_bf16_f32 v107, v38, v39
	v_cvt_pk_bf16_f32 v108, v40, v41
	v_cvt_pk_bf16_f32 v109, v42, v43
	v_cvt_pk_bf16_f32 v110, v44, v45
	v_cvt_pk_bf16_f32 v111, v46, v47
	v_cvt_pk_bf16_f32 v112, v48, v49
	v_cvt_pk_bf16_f32 v113, v50, v51
	v_cvt_pk_bf16_f32 v114, v52, v53
	v_cvt_pk_bf16_f32 v115, v54, v55
	v_cvt_pk_bf16_f32 v116, v56, v57
	v_cvt_pk_bf16_f32 v117, v58, v59
	v_cvt_pk_bf16_f32 v118, v60, v61
	v_cvt_pk_bf16_f32 v119, v62, v63
	ds_read_b128 v[184:187], v170 offset:13312
	ds_read_b128 v[188:191], v170 offset:19968
	ds_read_b128 v[192:195], v170 offset:13344
	ds_read_b128 v[196:199], v170 offset:20000
	s_barrier
	s_sub_u32 s13, s13, 1
	s_cmp_lg_u32 s13, 0
	s_cbranch_scc1 .Lat_loop
	ds_read_b128 v[200:203], v170 offset:13376
	ds_read_b128 v[204:207], v170 offset:20032
	s_waitcnt lgkmcnt(4)
	v_mfma_f32_32x32x16_bf16 v[32:47], v[184:187], v[80:83], v[64:79]
	v_mfma_f32_32x32x16_bf16 v[48:63], v[188:191], v[80:83], v[64:79]
	ds_read_b128 v[208:211], v170 offset:13408
	ds_read_b128 v[212:215], v170 offset:20064
	s_waitcnt lgkmcnt(4)
	v_mfma_f32_32x32x16_bf16 v[32:47], v[192:195], v[84:87], v[32:47]
	v_mfma_f32_32x32x16_bf16 v[48:63], v[196:199], v[84:87], v[48:63]
	ds_read_b128 v[184:187], v170 offset:13440
	ds_read_b128 v[188:191], v170 offset:20096
	s_waitcnt lgkmcnt(4)
	v_mfma_f32_32x32x16_bf16 v[32:47], v[200:203], v[88:91], v[32:47]
	v_mfma_f32_32x32x16_bf16 v[48:63], v[204:207], v[88:91], v[48:63]
	ds_read_b128 v[192:195], v170 offset:13472
	ds_read_b128 v[196:199], v170 offset:20128
	s_waitcnt lgkmcnt(4)
	v_mfma_f32_32x32x16_bf16 v[32:47], v[208:211], v[92:95], v[32:47]
	v_mfma_f32_32x32x16_bf16 v[48:63], v[212:215], v[92:95], v[48:63]
	ds_read_b64_tr_b16 v[148:149], v171 offset:0
	ds_read_b64_tr_b16 v[150:151], v171 offset:2048
	ds_read_b64_tr_b16 v[152:153], v171 offset:4096
	ds_read_b64_tr_b16 v[154:155], v171 offset:6144
	s_waitcnt lgkmcnt(6)
	v_mfma_f32_32x32x16_bf16 v[32:47], v[184:187], v[96:99], v[32:47]
	v_mfma_f32_32x32x16_bf16 v[48:63], v[188:191], v[96:99], v[48:63]
	ds_read_b64_tr_b16 v[156:157], v171 offset:8192
	ds_read_b64_tr_b16 v[158:159], v171 offset:10240
	ds_read_b64_tr_b16 v[216:217], v171 offset:12288
	ds_read_b64_tr_b16 v[218:219], v171 offset:14336
	s_waitcnt lgkmcnt(8)
	v_mfma_f32_32x32x16_bf16 v[32:47], v[192:195], v[100:103], v[32:47]
	v_mfma_f32_32x32x16_bf16 v[48:63], v[196:199], v[100:103], v[48:63]
	ds_read_b64_tr_b16 v[220:221], v171 offset:512
	ds_read_b64_tr_b16 v[222:223], v171 offset:2560
	ds_read_b64_tr_b16 v[224:225], v171 offset:4608
	ds_read_b64_tr_b16 v[226:227], v171 offset:6656
	s_waitcnt lgkmcnt(10)
	v_mfma_f32_32x32x16_bf16 v[0:15], v[104:107], v[148:151], v[0:15]
	s_waitcnt lgkmcnt(8)
	v_mfma_f32_32x32x16_bf16 v[0:15], v[108:111], v[152:155], v[0:15]
	ds_read_b64_tr_b16 v[236:237], v171 offset:8704
	ds_read_b64_tr_b16 v[238:239], v171 offset:10752
	ds_read_b64_tr_b16 v[240:241], v171 offset:12800
	ds_read_b64_tr_b16 v[242:243], v171 offset:14848
	s_waitcnt lgkmcnt(10)
	v_mfma_f32_32x32x16_bf16 v[0:15], v[112:115], v[156:159], v[0:15]
	s_waitcnt lgkmcnt(8)
	v_mfma_f32_32x32x16_bf16 v[0:15], v[116:119], v[216:219], v[0:15]
	s_waitcnt lgkmcnt(6)
	v_mfma_f32_32x32x16_bf16 v[16:31], v[104:107], v[220:223], v[16:31]
	s_waitcnt lgkmcnt(4)
	v_mfma_f32_32x32x16_bf16 v[16:31], v[108:111], v[224:227], v[16:31]
	s_waitcnt lgkmcnt(2)
	v_mfma_f32_32x32x16_bf16 v[16:31], v[112:115], v[236:239], v[16:31]
	s_waitcnt lgkmcnt(0)
	v_mfma_f32_32x32x16_bf16 v[16:31], v[116:119], v[240:243], v[16:31]
	s_barrier
	s_waitcnt vmcnt(3)
	ds_write_b128 v167, v[136:139] offset:39936
	ds_write_b128 v131, v[140:143] offset:49152
	ds_write_b128 v169, v[144:147] offset:39936
	v_exp_f32_e32 v32, v32
	v_exp_f32_e32 v48, v48
	v_exp_f32_e32 v33, v33
	v_exp_f32_e32 v49, v49
	v_exp_f32_e32 v34, v34
	v_exp_f32_e32 v50, v50
	v_exp_f32_e32 v35, v35
	v_exp_f32_e32 v51, v51
	v_exp_f32_e32 v36, v36
	v_exp_f32_e32 v52, v52
	v_exp_f32_e32 v37, v37
	v_exp_f32_e32 v53, v53
	v_exp_f32_e32 v38, v38
	v_exp_f32_e32 v54, v54
	v_exp_f32_e32 v39, v39
	v_exp_f32_e32 v55, v55
	v_exp_f32_e32 v40, v40
	v_exp_f32_e32 v56, v56
	v_exp_f32_e32 v41, v41
	v_exp_f32_e32 v57, v57
	v_exp_f32_e32 v42, v42
	v_exp_f32_e32 v58, v58
	v_exp_f32_e32 v43, v43
	v_exp_f32_e32 v59, v59
	v_exp_f32_e32 v44, v44
	v_exp_f32_e32 v60, v60
	v_exp_f32_e32 v45, v45
	v_exp_f32_e32 v61, v61
	v_exp_f32_e32 v46, v46
	v_exp_f32_e32 v62, v62
	v_exp_f32_e32 v47, v47
	v_exp_f32_e32 v63, v63
	s_waitcnt lgkmcnt(0)
	v_add_f32_e32 v175, v32, v33
	v_add_f32_e32 v174, v48, v49
	v_add_f32_e32 v175, v175, v34
	v_add_f32_e32 v174, v174, v50
	v_add_f32_e32 v175, v175, v35
	v_add_f32_e32 v174, v174, v51
	v_add_f32_e32 v175, v175, v36
	v_add_f32_e32 v174, v174, v52
	v_add_f32_e32 v175, v175, v37
	v_add_f32_e32 v174, v174, v53
	v_add_f32_e32 v175, v175, v38
	v_add_f32_e32 v174, v174, v54
	v_add_f32_e32 v175, v175, v39
	v_add_f32_e32 v174, v174, v55
	v_add_f32_e32 v175, v175, v40
	v_add_f32_e32 v174, v174, v56
	v_add_f32_e32 v175, v175, v41
	v_add_f32_e32 v174, v174, v57
	v_add_f32_e32 v175, v175, v42
	v_add_f32_e32 v174, v174, v58
	v_add_f32_e32 v175, v175, v43
	v_add_f32_e32 v174, v174, v59
	v_add_f32_e32 v175, v175, v44
	v_add_f32_e32 v174, v174, v60
	v_add_f32_e32 v175, v175, v45
	v_add_f32_e32 v174, v174, v61
	v_add_f32_e32 v175, v175, v46
	v_add_f32_e32 v174, v174, v62
	v_add_f32_e32 v175, v175, v47
	v_add_f32_e32 v174, v174, v63
	v_add_f32_e32 v175, v175, v174
	v_cmp_ge_f32_e32 vcc, s23, v175
	s_cmp_eq_u64 vcc, exec
	s_cbranch_scc0 .Lat_rare_t129
